# v33 + ffn_in k-loop with a single mid-iteration barrier (wait next stage + barrier + issue stage k+2 after the fragment reads; no head barrier for k>=1)
# baseline (speedup 1.0000x reference)
; DEVI f32x4 mfma16(bf16x8 a, bf16x8 b, f32x4 c) { return __builtin_amdgcn_mfma_f32_16x16x32_bf16(a, b, c, 0, 0, 0); }
;     ...
;     auto issue = [&](int kt, int st) {
;         glds_tile8(va, vb, a0p + (size_t)kt * kstepA, Btile + (size_t)kt * 64, __builtin_amdgcn_readfirstlane(lds0 + st * 32768));
;     };
;     const int sw0 = (quad ^ (l16 >> 1)) * 16;
;     const int aoffb = (wr * 64 + l16) * 128, boffb = 16384 + (wc * 64 + l16) * 128;
;     if (!first_issued) issue(0, 0);
; #pragma unroll 1
;     for (int kt = 0; kt < nk; ++kt) {
;         asm volatile("s_waitcnt vmcnt(0)\n\ts_barrier" ::: "memory");
;         if (kt + 1 < nk) issue(kt + 1, (kt + 1) & 1);
;         const unsigned char* cs = sbase + (kt & 1) * 32768;
;         bf16x8 af0[4], bf0[4], af1[4], bf1[4];
; #pragma unroll
;         for (int i = 0; i < 4; ++i) { af0[i] = *(const bf16x8*)(cs + aoffb + i * 2048 + sw0); bf0[i] = *(const bf16x8*)(cs + boffb + i * 2048 + sw0); }
; #pragma unroll
;         for (int i = 0; i < 4; ++i) { af1[i] = *(const bf16x8*)(cs + aoffb + i * 2048 + (sw0 ^ 64)); bf1[i] = *(const bf16x8*)(cs + boffb + i * 2048 + (sw0 ^ 64)); }
;         __builtin_amdgcn_sched_barrier(0);
; #pragma unroll
;         for (int i = 0; i < 4; ++i)
; #pragma unroll
;             for (int j = 0; j < 4; ++j) acc[i][j] = SWAP ? mfma16(bf0[j], af0[i], acc[i][j]) : mfma16(af0[i], bf0[j], acc[i][j]);
;         __builtin_amdgcn_sched_barrier(0);
; #pragma unroll
;         for (int i = 0; i < 4; ++i)
; #pragma unroll
;             for (int j = 0; j < 4; ++j) acc[i][j] = SWAP ? mfma16(bf1[j], af1[i], acc[i][j]) : mfma16(af1[i], bf1[j], acc[i][j]);
.LBB0_788:
	s_and_b32 s24, s31, 0x8000
	v_add_u32_e32 v108, s24, v73
	v_or_b32_e32 v109, s24, v74
	v_add_u32_e32 v96, v108, v72
	v_add_u32_e32 v104, v109, v72
	v_add_u32_e32 v128, v108, v75
	ds_read_b128 v[76:79], v96
	ds_read_b128 v[80:83], v96 offset:2048
	ds_read_b128 v[84:87], v104 offset:16384
	ds_read_b128 v[88:91], v104 offset:18432
	ds_read_b128 v[92:95], v96 offset:4096
	ds_read_b128 v[96:99], v96 offset:6144
	ds_read_b128 v[100:103], v104 offset:20480
	ds_read_b128 v[104:107], v104 offset:22528
	v_add_u32_e32 v132, v109, v75
	ds_read_b128 v[108:111], v128
	ds_read_b128 v[112:115], v128 offset:2048
	ds_read_b128 v[116:119], v132 offset:16384
	ds_read_b128 v[120:123], v132 offset:18432
	ds_read_b128 v[124:127], v128 offset:4096
	ds_read_b128 v[128:131], v128 offset:6144
	ds_read_b128 v[138:141], v132 offset:20480
	ds_read_b128 v[158:161], v132 offset:22528
	s_waitcnt lgkmcnt(13)
	v_mfma_f32_16x16x32_bf16 v[58:61], v[84:87], v[76:79], v[58:61]
	s_waitcnt lgkmcnt(12)
	v_mfma_f32_16x16x32_bf16 v[62:65], v[88:91], v[76:79], v[62:65]
	s_waitcnt lgkmcnt(9)
	v_mfma_f32_16x16x32_bf16 v[50:53], v[100:103], v[76:79], v[50:53]
	s_waitcnt lgkmcnt(8)
	v_mfma_f32_16x16x32_bf16 v[54:57], v[104:107], v[76:79], v[54:57]
	v_mfma_f32_16x16x32_bf16 v[42:45], v[84:87], v[80:83], v[42:45]
	v_mfma_f32_16x16x32_bf16 v[46:49], v[88:91], v[80:83], v[46:49]
	v_mfma_f32_16x16x32_bf16 v[34:37], v[100:103], v[80:83], v[34:37]
	v_mfma_f32_16x16x32_bf16 v[38:41], v[104:107], v[80:83], v[38:41]
	v_mfma_f32_16x16x32_bf16 v[26:29], v[84:87], v[92:95], v[26:29]
	v_mfma_f32_16x16x32_bf16 v[30:33], v[88:91], v[92:95], v[30:33]
	v_mfma_f32_16x16x32_bf16 v[18:21], v[100:103], v[92:95], v[18:21]
	v_mfma_f32_16x16x32_bf16 v[22:25], v[104:107], v[92:95], v[22:25]
	v_mfma_f32_16x16x32_bf16 v[6:9], v[84:87], v[96:99], v[6:9]
	v_mfma_f32_16x16x32_bf16 v[14:17], v[88:91], v[96:99], v[14:17]
	v_mfma_f32_16x16x32_bf16 v[2:5], v[100:103], v[96:99], v[2:5]
	v_mfma_f32_16x16x32_bf16 v[10:13], v[104:107], v[96:99], v[10:13]
	s_add_u32 s10, s10, 0x80
	s_waitcnt lgkmcnt(5)
	v_mfma_f32_16x16x32_bf16 v[58:61], v[116:119], v[108:111], v[58:61]
	s_addc_u32 s11, s11, 0
	s_add_u32 s14, s14, 0x80
	s_addc_u32 s15, s15, 0
	s_waitcnt lgkmcnt(4)
	v_mfma_f32_16x16x32_bf16 v[62:65], v[120:123], v[108:111], v[62:65]
	s_mov_b32 s31, s34
	s_waitcnt lgkmcnt(1)
	v_mfma_f32_16x16x32_bf16 v[50:53], v[138:141], v[108:111], v[50:53]
	s_waitcnt lgkmcnt(0)
	v_mfma_f32_16x16x32_bf16 v[54:57], v[158:161], v[108:111], v[54:57]
	s_waitcnt vmcnt(0)
	s_barrier
	s_cmp_lt_u32 s31, 0x78000
	s_cbranch_scc0 .Lffn_nomid
	s_add_i32 s24, s31, 0x8000
	s_and_b32 s24, s24, 0x8000
	s_add_i32 s24, s27, s24
	s_mov_b32 s25, m0
	s_mov_b32 m0, s24
	s_nop 0
	global_load_lds_dwordx4 v0, s[14:15]
	s_add_u32 m0, m0, 0x1000
	s_nop 0
	global_load_lds_dwordx4 v68, s[14:15]
	s_add_u32 m0, m0, 0x1000
	s_nop 0
	global_load_lds_dwordx4 v69, s[14:15]
	s_add_u32 m0, m0, 0x1000
	s_nop 0
	global_load_lds_dwordx4 v71, s[14:15]
	s_add_u32 m0, m0, 0x1000
	s_nop 0
	global_load_lds_dwordx4 v0, s[10:11]
	s_add_u32 m0, m0, 0x1000
	s_nop 0
	global_load_lds_dwordx4 v68, s[10:11]
	s_add_u32 m0, m0, 0x1000
	s_nop 0
	global_load_lds_dwordx4 v69, s[10:11]
	s_add_u32 m0, m0, 0x1000
	s_nop 0
	global_load_lds_dwordx4 v71, s[10:11]
	s_mov_b32 m0, s25

; #define TIDX tid_()
; #define LAS __attribute__((address_space(3)))
; DEVI int wave_() { return __builtin_amdgcn_readfirstlane(tid_() >> 6); }
;     ...
;     for (int kt = 0; kt < nk; ++kt) {
;         asm volatile("s_waitcnt vmcnt(0)\n\ts_barrier" ::: "memory");
;         if (kt + 1 < nk) issue(kt + 1, (kt + 1) & 1);
;     ...
;     __syncthreads();
; }
; DEVI void gemm_issue0(const bf16_t* Ab, int lda, const bf16_t* Btile, int ldb, bf16_t* smem) {
;     const int tid = TIDX, wave = wave_();
;     const unsigned lds0 = (unsigned)(size_t)((LAS unsigned char*)smem) + (unsigned)wave * 1024u;
;     unsigned va[4], vb[4];
; #pragma unroll
;     for (int j = 0; j < 4; ++j) {
;         const int R = j * 32 + (tid >> 3), c = (tid & 7) ^ ((R >> 1) & 7);
;         va[j] = (unsigned)(((size_t)R * lda + c * 8) * 2);
;         vb[j] = (unsigned)(((size_t)R * ldb + c * 8) * 2);
;     }
;     glds_tile8(va, vb, Ab, Btile, __builtin_amdgcn_readfirstlane(lds0));
; }
; DEVI bool tile_map(int it, int NTN, int& tm, int& tn) {
;     const int G = gridDim.x;
;     if ((G & 7) != 0) { const int t = blockIdx.x + it * G; if (t >= 128 * NTN) return false; tm = t / NTN; tn = t % NTN; return true; }
.Lffn_bar2:
	s_barrier
	s_and_b32 s24, s34, 0x8000
	s_add_i32 s24, s27, s24
	s_mov_b32 s25, m0
	s_mov_b32 m0, s24
	s_nop 0
	global_load_lds_dwordx4 v0, s[14:15]
	s_add_u32 m0, m0, 0x1000
	s_nop 0
	global_load_lds_dwordx4 v68, s[14:15]
	s_add_u32 m0, m0, 0x1000
	s_nop 0
	global_load_lds_dwordx4 v69, s[14:15]
	s_add_u32 m0, m0, 0x1000
	s_nop 0
	global_load_lds_dwordx4 v71, s[14:15]
	s_add_u32 m0, m0, 0x1000
	s_nop 0
	global_load_lds_dwordx4 v0, s[10:11]
	s_add_u32 m0, m0, 0x1000
	s_nop 0
	global_load_lds_dwordx4 v68, s[10:11]
	s_add_u32 m0, m0, 0x1000
	s_nop 0
	global_load_lds_dwordx4 v69, s[10:11]
	s_add_u32 m0, m0, 0x1000
	s_nop 0
	global_load_lds_dwordx4 v71, s[10:11]
	s_mov_b32 m0, s25
	s_branch .LBB0_788
.Lffn_k1:
	s_branch .LBB0_788
.LBB0_793:
	s_andn2_b64 vcc, exec, s[0:1]
	s_add_i32 s17, s17, 1
	s_waitcnt vmcnt(63) expcnt(7) lgkmcnt(15)
	s_barrier
	s_cbranch_vccnz .LBB0_799
	s_mul_i32 s11, s17, s4
	s_add_i32 s11, s11, s2
	s_mov_b32 s10, 0
	s_mov_b64 s[34:35], 0
	s_cmpk_gt_i32 s11, 0x15ff
	s_mov_b64 s[24:25], 0
	s_mov_b32 s14, 0
	s_cbranch_scc1 .LBB0_796
	s_mul_hi_i32 s10, s11, 0x2e8ba2e9
	s_lshr_b32 s14, s10, 31
	s_ashr_i32 s10, s10, 3
	s_add_i32 s14, s10, s14
	s_mul_i32 s10, s14, 44
	s_sub_i32 s10, s11, s10
	s_mov_b64 s[24:25], -1
